# LRU carry chain: all segment pairs read in one batch
# baseline (speedup 1.0000x reference)
.LBB0_1094:
	s_lshl_b32 s15, s11, 7
	s_mov_b64 s[0:1], s[22:23]
	v_add_u32_e32 v82, s15, v130
	s_add_u32 s8, s0, 0x7a00000
	v_max_i32_e32 v56, 3, v82
	s_addc_u32 s9, s1, 0
	v_add_u32_e32 v112, -3, v56
	v_lshl_add_u64 v[56:57], s[20:21], 0, v[112:113]
	v_mov_b64_e32 v[72:73], s[8:9]
	v_mad_u64_u32 v[58:59], s[0:1], v56, s33, v[72:73]
	v_mad_i32_i24 v59, v57, s33, v59
	v_mov_b32_e32 v107, v113
	v_lshl_add_u64 v[56:57], v[58:59], 0, v[106:107]
	v_add_co_u32_e32 v56, vcc, s74, v56
	v_max_i32_e32 v74, -1, v82
	s_nop 0
	v_addc_co_u32_e32 v57, vcc, 0, v57, vcc
	s_waitcnt vmcnt(16)
	v_mov_b32_e32 v64, v228
	v_mov_b32_e32 v65, v229
	v_mov_b32_e32 v66, v230
	v_mov_b32_e32 v67, v231
	v_or_b32_e32 v56, 1, v82
	v_max_i32_e32 v56, 3, v56
	v_add_u32_e32 v112, -3, v56
	v_lshl_add_u64 v[56:57], s[20:21], 0, v[112:113]
	v_mad_u64_u32 v[58:59], s[0:1], v56, s33, v[72:73]
	v_mad_i32_i24 v59, v57, s33, v59
	v_lshl_add_u64 v[56:57], v[58:59], 0, v[106:107]
	v_add_co_u32_e32 v56, vcc, s74, v56
	v_cmp_lt_i32_e64 s[2:3], 2, v82
	s_nop 0
	v_addc_co_u32_e32 v57, vcc, 0, v57, vcc
	v_mov_b32_e32 v68, v232
	v_mov_b32_e32 v69, v233
	v_mov_b32_e32 v70, v234
	v_mov_b32_e32 v71, v235
	v_max_i32_e32 v56, 1, v82
	v_add_u32_e32 v112, -1, v56
	v_lshl_add_u64 v[56:57], s[20:21], 0, v[112:113]
	v_max_i32_e32 v112, 0, v82
	v_lshl_add_u64 v[60:61], s[20:21], 0, v[112:113]
	v_add_u32_e32 v112, 1, v74
	v_lshl_add_u64 v[74:75], s[20:21], 0, v[112:113]
	v_mad_u64_u32 v[58:59], s[0:1], v56, s33, v[72:73]
	v_mad_u64_u32 v[62:63], s[0:1], v60, s33, v[72:73]
	v_mad_u64_u32 v[72:73], s[0:1], v74, s33, v[72:73]
	v_mad_i32_i24 v73, v75, s33, v73
	v_lshl_add_u64 v[72:73], v[72:73], 0, v[106:107]
	v_add_co_u32_e64 v72, s[0:1], s74, v72
	v_mad_i32_i24 v59, v57, s33, v59
	s_nop 0
	v_addc_co_u32_e64 v73, s[0:1], 0, v73, s[0:1]
	v_mov_b32_e32 v72, v236
	v_mov_b32_e32 v73, v237
	v_mov_b32_e32 v74, v238
	v_mov_b32_e32 v75, v239
	v_lshl_add_u64 v[56:57], v[58:59], 0, v[106:107]
	v_add_co_u32_e32 v56, vcc, s74, v56
	v_mad_i32_i24 v63, v61, s33, v63
	s_nop 0
	v_addc_co_u32_e32 v57, vcc, 0, v57, vcc
	v_lshl_add_u64 v[60:61], v[62:63], 0, v[106:107]
	v_add_co_u32_e32 v60, vcc, s74, v60
	v_mov_b32_e32 v56, v240
	v_mov_b32_e32 v57, v241
	v_mov_b32_e32 v58, v242
	v_mov_b32_e32 v59, v243
	s_nop 0
	v_addc_co_u32_e32 v61, vcc, 0, v61, vcc
	v_mov_b32_e32 v60, v244
	v_mov_b32_e32 v61, v245
	v_mov_b32_e32 v62, v246
	v_mov_b32_e32 v63, v247
	v_cmp_lt_i32_e32 vcc, -2, v82
	v_cmp_lt_i32_e64 s[0:1], -1, v82
	s_nop 0
	v_cndmask_b32_e64 v83, 0, v67, s[2:3]
	v_cndmask_b32_e64 v64, 0, v64, s[2:3]
	s_nop 0
	v_cndmask_b32_e32 v107, 0, v72, vcc
	v_cndmask_b32_e32 v109, 0, v73, vcc
	v_cndmask_b32_e32 v112, 0, v74, vcc
	v_cndmask_b32_e32 v151, 0, v75, vcc
	v_cmp_lt_i32_e32 vcc, 1, v82
	v_lshlrev_b32_e32 v74, 16, v64
	v_lshlrev_b32_e32 v72, 16, v83
	v_cndmask_b32_e32 v67, 0, v68, vcc
	v_lshlrev_b32_e32 v75, 16, v67
	v_pk_mul_f32 v[76:77], v[104:105], v[74:75]
	v_cndmask_b32_e32 v84, 0, v71, vcc
	v_add_f32_e32 v68, v48, v76
	v_add_f32_e32 v74, v68, v77
	v_and_b32_e32 v77, 0xffff0000, v67
	v_and_b32_e32 v76, 0xffff0000, v64
	v_pk_mul_f32 v[80:81], v[40:41], v[76:77]
	v_cndmask_b32_e64 v67, 0, v65, s[2:3]
	v_add_f32_e32 v64, v49, v80
	v_cndmask_b32_e32 v71, 0, v69, vcc
	v_add_f32_e32 v152, v64, v81
	v_lshlrev_b32_e32 v65, 16, v71
	v_lshlrev_b32_e32 v64, 16, v67
	v_pk_mul_f32 v[68:69], v[100:101], v[64:65]
	v_lshlrev_b32_e32 v73, 16, v84
	v_add_f32_e32 v64, v50, v68
	v_add_f32_e32 v64, v64, v69
	v_and_b32_e32 v69, 0xffff0000, v71
	v_and_b32_e32 v68, 0xffff0000, v67
	v_pk_mul_f32 v[78:79], v[92:93], v[72:73]
	v_pk_mul_f32 v[80:81], v[42:43], v[68:69]
	v_add_f32_e32 v72, v54, v78
	v_add_f32_e32 v67, v51, v80
	v_cndmask_b32_e64 v78, 0, v66, s[2:3]
	v_cndmask_b32_e32 v80, 0, v70, vcc
	v_add_f32_e32 v153, v67, v81
	v_lshlrev_b32_e32 v67, 16, v80
	v_lshlrev_b32_e32 v66, 16, v78
	v_pk_mul_f32 v[70:71], v[96:97], v[66:67]
	v_cmp_lt_i32_e32 vcc, 0, v82
	v_add_f32_e32 v66, v52, v70
	v_add_f32_e32 v66, v66, v71
	v_and_b32_e32 v71, 0xffff0000, v80
	v_and_b32_e32 v70, 0xffff0000, v78
	v_pk_mul_f32 v[80:81], v[36:37], v[70:71]
	v_add_f32_e32 v72, v72, v79
	v_add_f32_e32 v78, v53, v80
	v_add_f32_e32 v154, v78, v81
	v_and_b32_e32 v79, 0xffff0000, v84
	v_and_b32_e32 v78, 0xffff0000, v83
	s_nop 0
	v_cndmask_b32_e64 v60, 0, v60, s[0:1]
	v_cndmask_b32_e32 v56, 0, v56, vcc
	v_pk_mul_f32 v[80:81], v[38:39], v[78:79]
	v_lshlrev_b32_e32 v84, 16, v56
	v_lshlrev_b32_e32 v85, 16, v60
	v_add_f32_e32 v80, v55, v80
	v_cndmask_b32_e64 v156, 0, v63, s[0:1]
	v_cndmask_b32_e32 v59, 0, v59, vcc
	v_pk_mul_f32 v[86:87], v[102:103], v[84:85]
	v_add_f32_e32 v155, v80, v81
	v_lshlrev_b32_e32 v80, 16, v59
	v_lshlrev_b32_e32 v81, 16, v156
	v_add_f32_e32 v63, v74, v86
	v_pk_mul_f32 v[82:83], v[90:91], v[80:81]
	v_add_f32_e32 v74, v63, v87
	v_and_b32_e32 v87, 0xffff0000, v60
	v_and_b32_e32 v86, 0xffff0000, v56
	v_add_f32_e32 v72, v72, v82
	v_pk_mul_f32 v[110:111], v[44:45], v[86:87]
	v_cndmask_b32_e64 v63, 0, v61, s[0:1]
	v_cndmask_b32_e32 v82, 0, v57, vcc
	v_add_f32_e32 v56, v152, v110
	v_lshlrev_b32_e32 v60, 16, v82
	v_lshlrev_b32_e32 v61, 16, v63
	v_add_f32_e32 v157, v56, v111
	v_pk_mul_f32 v[56:57], v[98:99], v[60:61]
	v_and_b32_e32 v111, 0xffff0000, v63
	v_add_f32_e32 v56, v64, v56
	v_and_b32_e32 v110, 0xffff0000, v82
	v_add_f32_e32 v64, v56, v57
	v_pk_mul_f32 v[56:57], v[46:47], v[110:111]
	v_cndmask_b32_e64 v82, 0, v62, s[0:1]
	v_cndmask_b32_e32 v58, 0, v58, vcc
	v_add_f32_e32 v56, v153, v56
	v_lshlrev_b32_e32 v62, 16, v58
	v_lshlrev_b32_e32 v63, 16, v82
	v_add_f32_e32 v158, v56, v57
	v_pk_mul_f32 v[56:57], v[94:95], v[62:63]
	v_and_b32_e32 v153, 0xffff0000, v82
	v_add_f32_e32 v56, v66, v56
	v_and_b32_e32 v152, 0xffff0000, v58
	v_add_f32_e32 v66, v56, v57
	v_pk_mul_f32 v[56:57], v[32:33], v[152:153]
	v_add_f32_e32 v72, v72, v83
	v_add_f32_e32 v56, v154, v56
	v_and_b32_e32 v83, 0xffff0000, v156
	v_and_b32_e32 v82, 0xffff0000, v59
	v_add_f32_e32 v58, v56, v57
	v_pk_mul_f32 v[56:57], v[34:35], v[82:83]
	s_add_u32 s0, s12, s15
	v_add_f32_e32 v56, v155, v56
	v_add_f32_e32 v59, v56, v57
	v_cvt_pk_bf16_f32 v56, v74, v157
	v_cvt_pk_bf16_f32 v57, v64, v158
	v_cvt_pk_bf16_f32 v58, v66, v58
	v_cvt_pk_bf16_f32 v59, v72, v59
	ds_write_b128 v142, v[56:59] offset:18432
	v_pk_mov_b32 v[56:57], v[74:75], v[84:85] op_sel:[1,0]
	v_and_b32_e32 v59, 0xffff0000, v107
	v_pk_mul_f32 v[56:57], v[104:105], v[56:57]
	v_and_b32_e32 v75, 0xffff0000, v151
	v_add_f32_e32 v56, v48, v56
	v_add_f32_e32 v58, v56, v57
	v_pk_mov_b32 v[56:57], v[76:77], v[86:87] op_sel:[1,0]
	s_addc_u32 s1, s13, 0
	v_pk_mul_f32 v[56:57], v[40:41], v[56:57]
	s_mulk_i32 s1, 0x2400
	v_add_f32_e32 v56, v49, v56
	v_add_f32_e32 v64, v56, v57
	v_pk_mov_b32 v[56:57], v[64:65], v[60:61] op_sel:[1,0]
	v_lshlrev_b32_e32 v65, 16, v109
	v_pk_mul_f32 v[56:57], v[100:101], v[56:57]
	s_mul_hi_u32 s2, s0, 0x2400
	v_add_f32_e32 v56, v50, v56
	v_add_f32_e32 v60, v56, v57
	v_pk_mov_b32 v[56:57], v[68:69], v[110:111] op_sel:[1,0]
	v_lshlrev_b32_e32 v69, 16, v112
	v_pk_mul_f32 v[56:57], v[42:43], v[56:57]
	s_add_i32 s2, s2, s1
	v_add_f32_e32 v56, v51, v56
	v_add_f32_e32 v68, v56, v57
	v_pk_mov_b32 v[56:57], v[66:67], v[62:63] op_sel:[1,0]
	v_and_b32_e32 v67, 0xffff0000, v109
	v_pk_mul_f32 v[56:57], v[96:97], v[56:57]
	v_mov_b32_e32 v66, v111
	v_add_f32_e32 v56, v52, v56
	v_add_f32_e32 v62, v56, v57
	v_pk_mov_b32 v[56:57], v[70:71], v[152:153] op_sel:[1,0]
	v_and_b32_e32 v71, 0xffff0000, v112
	v_pk_mul_f32 v[56:57], v[36:37], v[56:57]
	v_mov_b32_e32 v70, v153
	v_add_f32_e32 v56, v53, v56
	v_add_f32_e32 v72, v56, v57
	v_pk_mov_b32 v[56:57], v[72:73], v[80:81] op_sel:[1,0]
	v_lshlrev_b32_e32 v73, 16, v151
	v_pk_mul_f32 v[56:57], v[92:93], v[56:57]
	v_add_u32_e32 v80, v132, v131
	v_add_f32_e32 v56, v54, v56
	v_add_f32_e32 v74, v56, v57
	v_pk_mov_b32 v[56:57], v[78:79], v[82:83] op_sel:[1,0]
	s_mulk_i32 s0, 0x2400
	v_pk_mul_f32 v[56:57], v[38:39], v[56:57]
	s_add_u32 s0, s8, s0
	v_add_f32_e32 v56, v55, v56
	v_add_f32_e32 v76, v56, v57
	v_lshlrev_b32_e32 v57, 16, v107
	v_mov_b32_e32 v56, v85
	v_pk_mul_f32 v[56:57], v[102:103], v[56:57]
	s_addc_u32 s1, s9, s2
	v_add_f32_e32 v56, v58, v56
	v_mov_b32_e32 v58, v87
	v_add_f32_e32 v77, v56, v57
	v_pk_mul_f32 v[56:57], v[44:45], v[58:59]
	s_add_u32 s0, s0, s14
	v_add_f32_e32 v56, v64, v56
	v_mov_b32_e32 v64, v61
	v_add_f32_e32 v58, v56, v57
	v_pk_mul_f32 v[56:57], v[98:99], v[64:65]
	s_addc_u32 s1, s1, 0
	v_add_f32_e32 v56, v60, v56
	v_add_f32_e32 v59, v56, v57
	v_pk_mul_f32 v[56:57], v[46:47], v[66:67]
	v_mov_b32_e32 v109, v113
	v_add_f32_e32 v56, v68, v56
	v_mov_b32_e32 v68, v63
	v_add_f32_e32 v60, v56, v57
	v_pk_mul_f32 v[56:57], v[94:95], v[68:69]
	s_nop 0
	v_add_f32_e32 v56, v62, v56
	v_add_f32_e32 v61, v56, v57
	v_pk_mul_f32 v[56:57], v[32:33], v[70:71]
	s_nop 0
	v_add_f32_e32 v56, v72, v56
	v_mov_b32_e32 v72, v81
	v_add_f32_e32 v62, v56, v57
	v_pk_mul_f32 v[56:57], v[90:91], v[72:73]
	s_nop 0
	v_add_f32_e32 v56, v74, v56
	v_mov_b32_e32 v74, v83
	v_add_f32_e32 v63, v56, v57
	v_pk_mul_f32 v[56:57], v[34:35], v[74:75]
	s_nop 0
	v_add_f32_e32 v56, v76, v56
	v_add_f32_e32 v64, v56, v57
	v_cvt_pk_bf16_f32 v56, v77, v58
	v_cvt_pk_bf16_f32 v57, v59, v60
	v_cvt_pk_bf16_f32 v58, v61, v62
	v_cvt_pk_bf16_f32 v59, v63, v64
	ds_write_b128 v143, v[56:59] offset:18432
	s_waitcnt lgkmcnt(0)
	s_barrier
	s_add_i32 s98, s11, 1
	s_min_u32 s98, s98, 15
	s_lshl_b32 s98, s98, 7
	v_add_u32_e32 v172, s98, v130
	v_add_u32_e32 v173, 0x7a01c00, v106
	v_add_u32_e32 v174, -3, v172
	v_max_i32_e32 v174, 0, v174
	v_add_u32_e32 v174, s20, v174
	v_mad_u32_u24 v174, v174, s33, v173
	global_load_dwordx4 v[228:231], v174, s[22:23]
	v_add_u32_e32 v175, -2, v172
	v_max_i32_e32 v175, 0, v175
	v_add_u32_e32 v175, s20, v175
	v_mad_u32_u24 v175, v175, s33, v173
	global_load_dwordx4 v[232:235], v175, s[22:23]
	v_add_u32_e32 v176, 1, v172
	v_max_i32_e32 v176, 0, v176
	v_add_u32_e32 v176, s20, v176
	v_mad_u32_u24 v176, v176, s33, v173
	global_load_dwordx4 v[236:239], v176, s[22:23]
	v_add_u32_e32 v177, -1, v172
	v_max_i32_e32 v177, 0, v177
	v_add_u32_e32 v177, s20, v177
	v_mad_u32_u24 v177, v177, s33, v173
	global_load_dwordx4 v[240:243], v177, s[22:23]
	v_add_u32_e32 v178, 0, v172
	v_max_i32_e32 v178, 0, v178
	v_add_u32_e32 v178, s20, v178
	v_mad_u32_u24 v178, v178, s33, v173
	global_load_dwordx4 v[244:247], v178, s[22:23]
	ds_read_b128 v[56:59], v80 offset:18432
	ds_read_b128 v[60:63], v144
	ds_read_b128 v[68:71], v144 offset:2304
	ds_read_b128 v[76:79], v144 offset:4608
	ds_read_b128 v[72:75], v144 offset:11520
	s_waitcnt lgkmcnt(1)
	v_mfma_f32_16x16x32_bf16 v[152:155], v[76:79], v[56:59], 0
	ds_read_b128 v[76:79], v144 offset:13824
	ds_read_b128 v[64:67], v144 offset:9216
	s_waitcnt lgkmcnt(1)
	v_mfma_f32_16x16x32_bf16 v[156:159], v[76:79], v[56:59], 0
	ds_read_b128 v[76:79], v144 offset:6912
	s_waitcnt lgkmcnt(0)
	v_mfma_f32_16x16x32_bf16 v[160:163], v[76:79], v[56:59], 0
	ds_read_b128 v[76:79], v144 offset:16128
	v_mfma_f32_16x16x32_bf16 v[60:63], v[60:63], v[56:59], 0
	v_mfma_f32_16x16x32_bf16 v[64:67], v[64:67], v[56:59], 0
	v_mfma_f32_16x16x32_bf16 v[68:71], v[68:71], v[56:59], 0
	v_mfma_f32_16x16x32_bf16 v[72:75], v[72:75], v[56:59], 0
	s_waitcnt lgkmcnt(0)
	v_mfma_f32_16x16x32_bf16 v[164:167], v[76:79], v[56:59], 0
	ds_read_b128 v[168:171], v80 offset:18496
	ds_read_b128 v[56:59], v144 offset:64
	ds_read_b64 v[110:111], v145 offset:18432
	s_waitcnt lgkmcnt(1)
	v_mfma_f32_16x16x32_bf16 v[84:87], v[56:59], v[168:171], v[60:63]
	ds_read_b128 v[56:59], v144 offset:9280
	s_nop 1
	ds_read_b128 v[60:63], v144 offset:16192
	s_waitcnt lgkmcnt(1)
	v_mfma_f32_16x16x32_bf16 v[80:83], v[56:59], v[168:171], v[64:67]
	ds_read_b128 v[56:59], v144 offset:2368
	s_nop 0
	v_add_f32_e32 v84, v0, v84
	v_mul_f32_e32 v84, 0xbfb8aa3b, v84
	s_waitcnt lgkmcnt(0)
	v_mfma_f32_16x16x32_bf16 v[76:79], v[56:59], v[168:171], v[68:71]
	ds_read_b128 v[56:59], v144 offset:11584
	v_exp_f32_e32 v84, v84
	v_add_f32_e32 v80, v4, v80
	v_mul_f32_e32 v80, 0xbfb8aa3b, v80
	v_exp_f32_e32 v80, v80
	v_add_f32_e32 v84, 1.0, v84
	v_rcp_f32_e32 v107, v84
	s_waitcnt lgkmcnt(0)
	v_mfma_f32_16x16x32_bf16 v[72:75], v[56:59], v[168:171], v[72:75]
	ds_read_b128 v[56:59], v144 offset:4672
	v_add_f32_e32 v80, 1.0, v80
	v_mul_f32_e32 v107, v127, v107
	v_rcp_f32_e32 v84, v80
	v_mul_f32_e32 v80, 0x3fb8aa3b, v107
	v_add_f32_e32 v107, v107, v107
	v_mul_f32_e32 v107, 0x3fb8aa3b, v107
	v_add_f32_e32 v85, v1, v85
	v_exp_f32_e32 v107, v107
	v_mul_f32_e32 v85, 0xbfb8aa3b, v85
	v_exp_f32_e32 v85, v85
	v_add_f32_e32 v81, v5, v81
	v_sub_f32_e32 v107, 1.0, v107
	v_max_f32_e32 v107, 0, v107
	v_add_f32_e32 v85, 1.0, v85
	v_mul_f32_e32 v81, 0xbfb8aa3b, v81
	s_waitcnt lgkmcnt(0)
	v_mfma_f32_16x16x32_bf16 v[68:71], v[56:59], v[168:171], v[152:155]
	v_exp_f32_e32 v81, v81
	v_add_f32_e32 v86, v2, v86
	v_mul_f32_e32 v86, 0xbfb8aa3b, v86
	v_sqrt_f32_e32 v152, v107
	v_rcp_f32_e32 v107, v85
	v_add_f32_e32 v81, 1.0, v81
	v_rcp_f32_e32 v85, v81
	v_exp_f32_e32 v86, v86
	v_mul_f32_e32 v107, v126, v107
	v_mul_f32_e32 v81, 0x3fb8aa3b, v107
	v_add_f32_e32 v107, v107, v107
	v_mul_f32_e32 v107, 0x3fb8aa3b, v107
	v_exp_f32_e32 v107, v107
	v_add_f32_e32 v82, v6, v82
	v_add_f32_e32 v86, 1.0, v86
	v_mul_f32_e32 v82, 0xbfb8aa3b, v82
	v_sub_f32_e32 v107, 1.0, v107
	v_max_f32_e32 v107, 0, v107
	v_sqrt_f32_e32 v153, v107
	v_rcp_f32_e32 v107, v86
	v_exp_f32_e32 v82, v82
	v_add_f32_e32 v87, v3, v87
	v_mul_f32_e32 v87, 0xbfb8aa3b, v87
	v_mul_f32_e32 v107, v125, v107
	v_add_f32_e32 v82, 1.0, v82
	v_rcp_f32_e32 v86, v82
	v_mul_f32_e32 v82, 0x3fb8aa3b, v107
	v_add_f32_e32 v107, v107, v107
	v_mul_f32_e32 v107, 0x3fb8aa3b, v107
	v_exp_f32_e32 v107, v107
	v_exp_f32_e32 v87, v87
	v_add_f32_e32 v83, v7, v83
	v_mul_f32_e32 v83, 0xbfb8aa3b, v83
	v_sub_f32_e32 v107, 1.0, v107
	v_max_f32_e32 v107, 0, v107
	v_add_f32_e32 v87, 1.0, v87
	v_pk_mul_f32 v[84:85], v[84:85], v[152:153]
	v_sqrt_f32_e32 v152, v107
	v_rcp_f32_e32 v107, v87
	v_exp_f32_e32 v83, v83
	ds_read_b128 v[56:59], v144 offset:13888
	v_exp_f32_e32 v80, v80
	v_mul_f32_e32 v107, v124, v107
	v_add_f32_e32 v83, 1.0, v83
	v_rcp_f32_e32 v87, v83
	v_mul_f32_e32 v83, 0x3fb8aa3b, v107
	v_add_f32_e32 v107, v107, v107
	v_mul_f32_e32 v107, 0x3fb8aa3b, v107
	v_exp_f32_e32 v107, v107
	v_exp_f32_e32 v81, v81
	v_exp_f32_e32 v82, v82
	v_exp_f32_e32 v83, v83
	v_sub_f32_e32 v107, 1.0, v107
	v_max_f32_e32 v107, 0, v107
	v_sqrt_f32_e32 v153, v107
	v_add_f32_e32 v76, v8, v76
	v_add_f32_e32 v77, v9, v77
	v_mul_f32_e32 v76, 0xbfb8aa3b, v76
	v_mul_f32_e32 v77, 0xbfb8aa3b, v77
	v_exp_f32_e32 v76, v76
	v_exp_f32_e32 v77, v77
	v_lshlrev_b32_e32 v154, 16, v110
	v_and_b32_e32 v155, 0xffff0000, v110
	v_lshlrev_b32_e32 v110, 16, v111
	v_and_b32_e32 v111, 0xffff0000, v111
	v_pk_mul_f32 v[86:87], v[86:87], v[152:153]
	v_add_u32_e32 v107, v133, v137
	s_waitcnt lgkmcnt(0)
	v_mfma_f32_16x16x32_bf16 v[64:67], v[56:59], v[168:171], v[156:159]
	ds_read_b128 v[56:59], v144 offset:6976
	v_pk_mul_f32 v[84:85], v[84:85], v[154:155]
	v_pk_mul_f32 v[86:87], v[86:87], v[110:111]
	ds_write_b128 v107, v[80:83] offset:36864
	v_add_u32_e32 v80, v134, v137
	v_add_f32_e32 v78, v10, v78
	ds_write_b128 v80, v[84:87]
	v_add_f32_e32 v72, v12, v72
	v_add_f32_e32 v73, v13, v73
	v_mul_f32_e32 v78, 0xbfb8aa3b, v78
	ds_read_b64 v[80:81], v146 offset:18432
	v_add_f32_e32 v76, 1.0, v76
	v_mul_f32_e32 v72, 0xbfb8aa3b, v72
	v_add_f32_e32 v77, 1.0, v77
	v_mul_f32_e32 v73, 0xbfb8aa3b, v73
	v_exp_f32_e32 v78, v78
	v_rcp_f32_e32 v82, v76
	v_exp_f32_e32 v72, v72
	v_rcp_f32_e32 v83, v77
	v_exp_f32_e32 v73, v73
	v_add_f32_e32 v74, v14, v74
	v_add_f32_e32 v78, 1.0, v78
	v_mul_f32_e32 v74, 0xbfb8aa3b, v74
	v_add_f32_e32 v72, 1.0, v72
	v_mul_f32_e32 v82, v123, v82
	v_add_f32_e32 v73, 1.0, v73
	v_mul_f32_e32 v83, v122, v83
	s_waitcnt lgkmcnt(0)
	v_lshlrev_b32_e32 v84, 16, v80
	v_and_b32_e32 v85, 0xffff0000, v80
	v_rcp_f32_e32 v80, v78
	v_exp_f32_e32 v74, v74
	v_rcp_f32_e32 v76, v72
	v_mul_f32_e32 v72, 0x3fb8aa3b, v82
	v_add_f32_e32 v82, v82, v82
	v_rcp_f32_e32 v77, v73
	v_mul_f32_e32 v73, 0x3fb8aa3b, v83
	v_add_f32_e32 v83, v83, v83
	v_mul_f32_e32 v82, 0x3fb8aa3b, v82
	v_mul_f32_e32 v83, 0x3fb8aa3b, v83
	v_exp_f32_e32 v82, v82
	v_exp_f32_e32 v83, v83
	v_add_f32_e32 v74, 1.0, v74
	v_mul_f32_e32 v80, v121, v80
	v_rcp_f32_e32 v78, v74
	v_mul_f32_e32 v74, 0x3fb8aa3b, v80
	v_add_f32_e32 v80, v80, v80
	v_mul_f32_e32 v80, 0x3fb8aa3b, v80
	v_add_f32_e32 v79, v11, v79
	v_sub_f32_e32 v82, 1.0, v82
	v_sub_f32_e32 v83, 1.0, v83
	v_exp_f32_e32 v80, v80
	v_mul_f32_e32 v79, 0xbfb8aa3b, v79
	v_max_f32_e32 v82, 0, v82
	v_max_f32_e32 v83, 0, v83
	v_exp_f32_e32 v79, v79
	v_sqrt_f32_e32 v82, v82
	v_sqrt_f32_e32 v83, v83
	v_sub_f32_e32 v80, 1.0, v80
	v_add_f32_e32 v75, v15, v75
	v_max_f32_e32 v80, 0, v80
	v_add_f32_e32 v79, 1.0, v79
	v_mul_f32_e32 v75, 0xbfb8aa3b, v75
	v_pk_mul_f32 v[76:77], v[76:77], v[82:83]
	v_sqrt_f32_e32 v82, v80
	v_rcp_f32_e32 v80, v79
	v_exp_f32_e32 v75, v75
	v_exp_f32_e32 v72, v72
	v_exp_f32_e32 v73, v73
	v_mul_f32_e32 v80, v120, v80
	v_add_f32_e32 v75, 1.0, v75
	v_rcp_f32_e32 v79, v75
	v_mul_f32_e32 v75, 0x3fb8aa3b, v80
	v_add_f32_e32 v80, v80, v80
	v_mul_f32_e32 v80, 0x3fb8aa3b, v80
	v_exp_f32_e32 v80, v80
	v_exp_f32_e32 v74, v74
	v_exp_f32_e32 v75, v75
	v_add_f32_e32 v68, v16, v68
	v_sub_f32_e32 v80, 1.0, v80
	v_max_f32_e32 v80, 0, v80
	v_sqrt_f32_e32 v83, v80
	v_add_f32_e32 v69, v17, v69
	v_mul_f32_e32 v68, 0xbfb8aa3b, v68
	v_mul_f32_e32 v69, 0xbfb8aa3b, v69
	v_lshlrev_b32_e32 v80, 16, v81
	v_and_b32_e32 v81, 0xffff0000, v81
	v_pk_mul_f32 v[78:79], v[78:79], v[82:83]
	v_exp_f32_e32 v68, v68
	v_exp_f32_e32 v69, v69
	v_pk_mul_f32 v[78:79], v[78:79], v[80:81]
	v_add_u32_e32 v80, v133, v138
	v_pk_mul_f32 v[76:77], v[76:77], v[84:85]
	ds_write_b128 v80, v[72:75] offset:36864
	v_add_u32_e32 v72, v134, v138
	v_add_f32_e32 v70, v18, v70
	ds_write_b128 v72, v[76:79]
	v_add_f32_e32 v64, v20, v64
	v_add_f32_e32 v65, v21, v65
	v_mul_f32_e32 v70, 0xbfb8aa3b, v70
	ds_read_b64 v[72:73], v147 offset:18432
	v_add_f32_e32 v68, 1.0, v68
	v_mul_f32_e32 v64, 0xbfb8aa3b, v64
	v_add_f32_e32 v69, 1.0, v69
	v_mul_f32_e32 v65, 0xbfb8aa3b, v65
	v_exp_f32_e32 v70, v70
	v_rcp_f32_e32 v74, v68
	v_exp_f32_e32 v64, v64
	v_rcp_f32_e32 v75, v69
	v_exp_f32_e32 v65, v65
	v_add_f32_e32 v66, v22, v66
	v_add_f32_e32 v70, 1.0, v70
	v_mul_f32_e32 v66, 0xbfb8aa3b, v66
	v_add_f32_e32 v64, 1.0, v64
	v_mul_f32_e32 v74, v119, v74
	v_add_f32_e32 v65, 1.0, v65
	v_mul_f32_e32 v75, v118, v75
	s_waitcnt lgkmcnt(0)
	v_lshlrev_b32_e32 v76, 16, v72
	v_and_b32_e32 v77, 0xffff0000, v72
	v_rcp_f32_e32 v72, v70
	v_exp_f32_e32 v66, v66
	v_rcp_f32_e32 v68, v64
	v_mul_f32_e32 v64, 0x3fb8aa3b, v74
	v_add_f32_e32 v74, v74, v74
	v_rcp_f32_e32 v69, v65
	v_mul_f32_e32 v65, 0x3fb8aa3b, v75
	v_add_f32_e32 v75, v75, v75
	v_mul_f32_e32 v74, 0x3fb8aa3b, v74
	v_mul_f32_e32 v75, 0x3fb8aa3b, v75
	v_exp_f32_e32 v74, v74
	v_exp_f32_e32 v75, v75
	v_add_f32_e32 v66, 1.0, v66
	v_mul_f32_e32 v72, v117, v72
	v_rcp_f32_e32 v70, v66
	v_mul_f32_e32 v66, 0x3fb8aa3b, v72
	v_add_f32_e32 v72, v72, v72
	v_mul_f32_e32 v72, 0x3fb8aa3b, v72
	v_add_f32_e32 v71, v19, v71
	v_sub_f32_e32 v74, 1.0, v74
	v_sub_f32_e32 v75, 1.0, v75
	v_exp_f32_e32 v72, v72
	v_mul_f32_e32 v71, 0xbfb8aa3b, v71
	v_max_f32_e32 v74, 0, v74
	v_max_f32_e32 v75, 0, v75
	v_exp_f32_e32 v71, v71
	v_sqrt_f32_e32 v74, v74
	v_sqrt_f32_e32 v75, v75
	v_sub_f32_e32 v72, 1.0, v72
	v_add_f32_e32 v67, v23, v67
	v_max_f32_e32 v72, 0, v72
	v_add_f32_e32 v71, 1.0, v71
	v_mul_f32_e32 v67, 0xbfb8aa3b, v67
	v_pk_mul_f32 v[68:69], v[68:69], v[74:75]
	v_sqrt_f32_e32 v74, v72
	v_rcp_f32_e32 v72, v71
	v_exp_f32_e32 v67, v67
	v_mfma_f32_16x16x32_bf16 v[56:59], v[56:59], v[168:171], v[160:163]
	v_exp_f32_e32 v64, v64
	v_mul_f32_e32 v72, v116, v72
	v_add_f32_e32 v67, 1.0, v67
	v_rcp_f32_e32 v71, v67
	v_mul_f32_e32 v67, 0x3fb8aa3b, v72
	v_add_f32_e32 v72, v72, v72
	v_mul_f32_e32 v72, 0x3fb8aa3b, v72
	v_exp_f32_e32 v72, v72
	v_add_f32_e32 v56, v24, v56
	v_add_f32_e32 v57, v25, v57
	v_mul_f32_e32 v56, 0xbfb8aa3b, v56
	v_sub_f32_e32 v72, 1.0, v72
	v_max_f32_e32 v72, 0, v72
	v_mul_f32_e32 v57, 0xbfb8aa3b, v57
	v_sqrt_f32_e32 v75, v72
	v_exp_f32_e32 v56, v56
	v_exp_f32_e32 v57, v57
	v_exp_f32_e32 v65, v65
	v_exp_f32_e32 v66, v66
	v_exp_f32_e32 v67, v67
	v_add_f32_e32 v58, v26, v58
	v_mul_f32_e32 v58, 0xbfb8aa3b, v58
	v_lshlrev_b32_e32 v72, 16, v73
	v_and_b32_e32 v73, 0xffff0000, v73
	v_pk_mul_f32 v[70:71], v[70:71], v[74:75]
	v_add_f32_e32 v56, 1.0, v56
	v_add_f32_e32 v57, 1.0, v57
	v_exp_f32_e32 v58, v58
	v_pk_mul_f32 v[70:71], v[70:71], v[72:73]
	v_add_u32_e32 v72, v133, v139
	v_rcp_f32_e32 v56, v56
	v_rcp_f32_e32 v57, v57
	v_pk_mul_f32 v[68:69], v[68:69], v[76:77]
	ds_write_b128 v72, v[64:67] offset:36864
	v_add_u32_e32 v64, v134, v139
	v_mfma_f32_16x16x32_bf16 v[60:63], v[60:63], v[168:171], v[164:167]
	ds_write_b128 v64, v[68:71]
	ds_read_b64 v[64:65], v148 offset:18432
	v_add_f32_e32 v58, 1.0, v58
	v_mul_f32_e32 v66, v115, v56
	v_mul_f32_e32 v67, v114, v57
	v_rcp_f32_e32 v58, v58
	v_mul_f32_e32 v56, 0x3fb8aa3b, v66
	v_add_f32_e32 v66, v66, v66
	v_mul_f32_e32 v57, 0x3fb8aa3b, v67
	v_add_f32_e32 v67, v67, v67
	v_add_f32_e32 v60, v28, v60
	v_mul_f32_e32 v66, 0x3fb8aa3b, v66
	v_add_f32_e32 v61, v29, v61
	v_mul_f32_e32 v67, 0x3fb8aa3b, v67
	v_add_f32_e32 v59, v27, v59
	v_mul_f32_e32 v60, 0xbfb8aa3b, v60
	v_exp_f32_e32 v66, v66
	v_mul_f32_e32 v61, 0xbfb8aa3b, v61
	v_exp_f32_e32 v67, v67
	v_mul_f32_e32 v59, 0xbfb8aa3b, v59
	v_exp_f32_e32 v60, v60
	v_exp_f32_e32 v61, v61
	s_waitcnt lgkmcnt(0)
	v_lshlrev_b32_e32 v68, 16, v64
	v_and_b32_e32 v69, 0xffff0000, v64
	v_mul_f32_e32 v64, v89, v58
	v_exp_f32_e32 v59, v59
	v_mul_f32_e32 v58, 0x3fb8aa3b, v64
	v_add_f32_e32 v64, v64, v64
	v_mul_f32_e32 v64, 0x3fb8aa3b, v64
	v_sub_f32_e32 v66, 1.0, v66
	v_sub_f32_e32 v67, 1.0, v67
	v_exp_f32_e32 v64, v64
	v_add_f32_e32 v60, 1.0, v60
	v_max_f32_e32 v66, 0, v66
	v_add_f32_e32 v61, 1.0, v61
	v_max_f32_e32 v67, 0, v67
	v_add_f32_e32 v59, 1.0, v59
	v_rcp_f32_e32 v60, v60
	v_sqrt_f32_e32 v66, v66
	v_rcp_f32_e32 v61, v61
	v_sqrt_f32_e32 v67, v67
	v_rcp_f32_e32 v59, v59
	v_sub_f32_e32 v64, 1.0, v64
	v_max_f32_e32 v64, 0, v64
	v_pk_mul_f32 v[60:61], v[60:61], v[66:67]
	v_sqrt_f32_e32 v66, v64
	v_mul_f32_e32 v64, v128, v59
	v_mul_f32_e32 v59, 0x3fb8aa3b, v64
	v_add_f32_e32 v64, v64, v64
	v_add_f32_e32 v62, v30, v62
	v_add_f32_e32 v63, v31, v63
	v_mul_f32_e32 v64, 0x3fb8aa3b, v64
	v_mul_f32_e32 v62, 0xbfb8aa3b, v62
	v_mul_f32_e32 v63, 0xbfb8aa3b, v63
	v_exp_f32_e32 v64, v64
	v_exp_f32_e32 v62, v62
	v_exp_f32_e32 v63, v63
	v_exp_f32_e32 v56, v56
	v_sub_f32_e32 v64, 1.0, v64
	v_add_f32_e32 v62, 1.0, v62
	v_add_f32_e32 v63, 1.0, v63
	v_max_f32_e32 v64, 0, v64
	v_rcp_f32_e32 v62, v62
	v_rcp_f32_e32 v63, v63
	v_sqrt_f32_e32 v67, v64
	v_exp_f32_e32 v57, v57
	v_exp_f32_e32 v58, v58
	v_exp_f32_e32 v59, v59
	v_lshlrev_b32_e32 v64, 16, v65
	v_and_b32_e32 v65, 0xffff0000, v65
	v_pk_mul_f32 v[62:63], v[62:63], v[66:67]
	v_pk_mul_f32 v[60:61], v[60:61], v[68:69]
	v_pk_mul_f32 v[62:63], v[62:63], v[64:65]
	v_add_u32_e32 v64, v133, v140
	ds_write_b128 v64, v[56:59] offset:36864
	v_add_u32_e32 v56, v134, v140
	v_lshl_add_u64 v[66:67], s[0:1], 0, v[108:109]
	ds_write_b128 v56, v[60:63]
	v_add_co_u32_e32 v56, vcc, s16, v66
	s_waitcnt lgkmcnt(0)
	s_barrier
	s_nop 0
	v_addc_co_u32_e32 v57, vcc, 0, v67, vcc
	global_load_ushort v163, v108, s[0:1] offset:2048
	global_load_ushort v162, v[56:57], off offset:3072
	s_movk_i32 s0, 0x5000
	v_add_co_u32_e32 v56, vcc, s0, v66
	s_movk_i32 s0, 0x7000
	s_nop 0
	v_addc_co_u32_e32 v57, vcc, 0, v67, vcc
	global_load_ushort v161, v[56:57], off
	v_add_co_u32_e32 v56, vcc, s0, v66
	s_mov_b32 s0, 0x9000
	s_nop 0
	v_addc_co_u32_e32 v57, vcc, 0, v67, vcc
	global_load_ushort v160, v[56:57], off offset:1024
	v_add_co_u32_e32 v56, vcc, s0, v66
	s_mov_b32 s0, 0xb000
	s_nop 0
	v_addc_co_u32_e32 v57, vcc, 0, v67, vcc
	global_load_ushort v159, v[56:57], off offset:2048
	v_add_co_u32_e32 v56, vcc, s0, v66
	s_mov_b32 s0, 0xe000
	s_nop 0
	v_addc_co_u32_e32 v57, vcc, 0, v67, vcc
	global_load_ushort v158, v[56:57], off offset:3072
	v_add_co_u32_e32 v56, vcc, s0, v66
	s_mov_b32 s0, 0x10000
	s_nop 0
	v_addc_co_u32_e32 v57, vcc, 0, v67, vcc
	global_load_ushort v157, v[56:57], off
	v_add_co_u32_e32 v56, vcc, s0, v66
	s_mov_b32 s0, 0x12000
	s_nop 0
	v_addc_co_u32_e32 v57, vcc, 0, v67, vcc
	global_load_ushort v156, v[56:57], off offset:1024
	v_add_co_u32_e32 v56, vcc, s0, v66
	s_mov_b32 s0, 0x14000
	s_nop 0
	v_addc_co_u32_e32 v57, vcc, 0, v67, vcc
	global_load_ushort v155, v[56:57], off offset:2048
	v_add_co_u32_e32 v56, vcc, s0, v66
	s_mov_b32 s0, 0x17000
	s_nop 0
	v_addc_co_u32_e32 v57, vcc, 0, v67, vcc
	global_load_ushort v154, v[56:57], off offset:3072
	v_add_co_u32_e32 v56, vcc, s0, v66
	s_mov_b32 s0, 0x19000
	s_nop 0
	v_addc_co_u32_e32 v57, vcc, 0, v67, vcc
	global_load_ushort v153, v[56:57], off
	v_add_co_u32_e32 v56, vcc, s0, v66
	s_mov_b32 s0, 0x1b000
	s_nop 0
	v_addc_co_u32_e32 v57, vcc, 0, v67, vcc
	global_load_ushort v152, v[56:57], off offset:1024
	v_add_co_u32_e32 v56, vcc, s0, v66
	s_mov_b32 s0, 0x1d000
	s_nop 0
	v_addc_co_u32_e32 v57, vcc, 0, v67, vcc
	global_load_ushort v151, v[56:57], off offset:2048
	v_add_co_u32_e32 v56, vcc, s0, v66
	s_mov_b32 s0, 0x20000
	s_nop 0
	v_addc_co_u32_e32 v57, vcc, 0, v67, vcc
	global_load_ushort v112, v[56:57], off offset:3072
	v_add_co_u32_e32 v56, vcc, s0, v66
	s_mov_b32 s0, 0x22000
	s_nop 0
	v_addc_co_u32_e32 v57, vcc, 0, v67, vcc
	global_load_ushort v109, v[56:57], off
	v_add_co_u32_e32 v56, vcc, s0, v66
	v_add_u32_e32 v62, 0x9000, v149
	s_nop 0
	v_addc_co_u32_e32 v57, vcc, 0, v67, vcc
	global_load_ushort v107, v[56:57], off offset:1024
	ds_read_b32 v182, v149 offset:36864
	ds_read_b32 v166, v150
	ds_read_b32 v183, v149 offset:37136
	ds_read_b32 v167, v150 offset:272
	ds_read_b32 v184, v149 offset:37408
	ds_read_b32 v168, v150 offset:544
	ds_read_b32 v185, v149 offset:37680
	ds_read_b32 v169, v150 offset:816
	ds_read_b32 v186, v149 offset:37952
	ds_read_b32 v170, v150 offset:1088
	ds_read_b32 v187, v149 offset:38224
	ds_read_b32 v171, v150 offset:1360
	ds_read_b32 v188, v149 offset:38496
	ds_read_b32 v172, v150 offset:1632
	ds_read_b32 v189, v149 offset:38768
	ds_read_b32 v173, v150 offset:1904
	ds_read_b32 v208, v149 offset:39040
	ds_read_b32 v174, v150 offset:2176
	ds_read_b32 v209, v149 offset:39312
	ds_read_b32 v175, v150 offset:2448
	ds_read_b32 v210, v149 offset:39584
	ds_read_b32 v176, v150 offset:2720
	ds_read_b32 v211, v149 offset:39856
	ds_read_b32 v177, v150 offset:2992
	ds_read_b32 v212, v149 offset:40128
	ds_read_b32 v178, v150 offset:3264
	ds_read_b32 v213, v149 offset:40400
	ds_read_b32 v179, v150 offset:3536
	ds_read_b32 v252, v149 offset:40672
	ds_read_b32 v180, v150 offset:3808
	ds_read_b32 v253, v149 offset:40944
	ds_read_b32 v181, v150 offset:4080
	s_lshl_b32 s0, s11, 6
	s_and_b32 s0, s0, 64
	s_andn2_b64 vcc, exec, s[4:5]
	s_mov_b32 s1, s10
	s_waitcnt lgkmcnt(0)
	v_fma_f32 v166, 0, v182, v166
	v_fma_f32 v167, v166, v183, v167
	v_mul_f32_e32 v183, v182, v183
	v_fma_f32 v168, v167, v184, v168
	v_mul_f32_e32 v184, v183, v184
	v_fma_f32 v169, v168, v185, v169
	v_mul_f32_e32 v185, v184, v185
	v_fma_f32 v170, v169, v186, v170
	v_mul_f32_e32 v186, v185, v186
	v_fma_f32 v171, v170, v187, v171
	v_mul_f32_e32 v187, v186, v187
	v_fma_f32 v172, v171, v188, v172
	v_mul_f32_e32 v188, v187, v188
	v_fma_f32 v173, v172, v189, v173
	v_mul_f32_e32 v189, v188, v189
	v_fma_f32 v174, v173, v208, v174
	v_mul_f32_e32 v208, v189, v208
	v_fma_f32 v175, v174, v209, v175
	v_mul_f32_e32 v209, v208, v209
	v_fma_f32 v176, v175, v210, v176
	v_mul_f32_e32 v210, v209, v210
	v_fma_f32 v177, v176, v211, v177
	v_mul_f32_e32 v211, v210, v211
	v_fma_f32 v178, v177, v212, v178
	v_mul_f32_e32 v212, v211, v212
	v_fma_f32 v179, v178, v213, v179
	v_mul_f32_e32 v213, v212, v213
	v_fma_f32 v180, v179, v252, v180
	v_mul_f32_e32 v252, v213, v252
	v_fma_f32 v181, v180, v253, v181
	v_mul_f32_e32 v253, v252, v253
	ds_write_b32 v150, v166
	ds_write_b32 v150, v167 offset:272
	ds_write_b32 v149, v183 offset:37136
	ds_write_b32 v150, v168 offset:544
	ds_write_b32 v149, v184 offset:37408
	ds_write_b32 v150, v169 offset:816
	ds_write_b32 v149, v185 offset:37680
	ds_write_b32 v150, v170 offset:1088
	ds_write_b32 v149, v186 offset:37952
	ds_write_b32 v150, v171 offset:1360
	ds_write_b32 v149, v187 offset:38224
	ds_write_b32 v150, v172 offset:1632
	ds_write_b32 v149, v188 offset:38496
	ds_write_b32 v150, v173 offset:1904
	ds_write_b32 v149, v189 offset:38768
	ds_write_b32 v150, v174 offset:2176
	ds_write_b32 v149, v208 offset:39040
	ds_write_b32 v150, v175 offset:2448
	ds_write_b32 v149, v209 offset:39312
	ds_write_b32 v150, v176 offset:2720
	ds_write_b32 v149, v210 offset:39584
	ds_write_b32 v150, v177 offset:2992
	ds_write_b32 v149, v211 offset:39856
	ds_write_b32 v150, v178 offset:3264
	ds_write_b32 v149, v212 offset:40128
	ds_write_b32 v150, v179 offset:3536
	ds_write_b32 v149, v213 offset:40400
	ds_write_b32 v150, v180 offset:3808
	ds_write_b32 v149, v252 offset:40672
	ds_write_b32 v150, v181 offset:4080
	v_mov_b32_e32 v164, v253
	v_mov_b32_e32 v111, v181
	ds_write_b32 v149, v164 offset:40944
	ds_write_b32 v135, v164
	ds_write_b32 v136, v111
	s_waitcnt lgkmcnt(0)
	s_barrier
	ds_read_b32 v166, v150
	ds_read_b32 v182, v149 offset:36864
	ds_read_b32 v167, v150 offset:272
	ds_read_b32 v183, v149 offset:37136
	ds_read_b32 v168, v150 offset:544
	ds_read_b32 v184, v149 offset:37408
	ds_read_b32 v169, v150 offset:816
	ds_read_b32 v185, v149 offset:37680
	ds_read_b32 v170, v150 offset:1088
	ds_read_b32 v186, v149 offset:37952
	ds_read_b32 v171, v150 offset:1360
	ds_read_b32 v187, v149 offset:38224
	ds_read_b32 v172, v150 offset:1632
	ds_read_b32 v188, v149 offset:38496
	ds_read_b32 v173, v150 offset:1904
	ds_read_b32 v189, v149 offset:38768
	ds_read_b32 v174, v150 offset:2176
	ds_read_b32 v208, v149 offset:39040
	ds_read_b32 v175, v150 offset:2448
	ds_read_b32 v209, v149 offset:39312
	ds_read_b32 v176, v150 offset:2720
	ds_read_b32 v210, v149 offset:39584
	ds_read_b32 v177, v150 offset:2992
	ds_read_b32 v211, v149 offset:39856
	ds_read_b32 v178, v150 offset:3264
	ds_read_b32 v212, v149 offset:40128
	ds_read_b32 v179, v150 offset:3536
	ds_read_b32 v213, v149 offset:40400
	ds_read_b32 v180, v150 offset:3808
	ds_read_b32 v252, v149 offset:40672
	ds_read_b32 v181, v150 offset:4080
	ds_read_b32 v253, v149 offset:40944
	v_lshl_add_u32 v56, s0, 2, v129
	ds_read_b32 v110, v56
	s_cbranch_vccnz .LBB0_1096
	v_add_u32_e32 v57, 0xfffff800, v141
	ds_read_b32 v68, v57
	ds_read_b32 v69, v141
	ds_read_b32 v70, v57 offset:256
	ds_read_b32 v71, v141 offset:256
	ds_read_b32 v72, v57 offset:512
	ds_read_b32 v73, v141 offset:512
	ds_read_b32 v74, v57 offset:768
	ds_read_b32 v75, v141 offset:768
	ds_read_b32 v76, v57 offset:1024
	ds_read_b32 v77, v141 offset:1024
	ds_read_b32 v78, v57 offset:1280
	ds_read_b32 v79, v141 offset:1280
	ds_read_b32 v80, v57 offset:1536
	ds_read_b32 v81, v141 offset:1536
	s_waitcnt lgkmcnt(0)
	v_fma_f32 v110, v110, v68, v69
	s_cmp_eq_u32 s1, 1
	s_cbranch_scc1 .LBB0_1096
	v_fma_f32 v110, v110, v70, v71
	s_cmp_eq_u32 s1, 2
	s_cbranch_scc1 .LBB0_1096
	v_fma_f32 v110, v110, v72, v73
	s_cmp_eq_u32 s1, 3
	s_cbranch_scc1 .LBB0_1096
	v_fma_f32 v110, v110, v74, v75
	s_cmp_eq_u32 s1, 4
	s_cbranch_scc1 .LBB0_1096
	v_fma_f32 v110, v110, v76, v77
	s_cmp_eq_u32 s1, 5
	s_cbranch_scc1 .LBB0_1096
	v_fma_f32 v110, v110, v78, v79
	s_cmp_eq_u32 s1, 6
	s_cbranch_scc1 .LBB0_1096
	v_fma_f32 v110, v110, v80, v81
